# P0 publish: write-through sc1 stores for adaLN outputs, tables and bf16 weight copies, drop the two buffer_wbl2 release write-backs
# speedup vs baseline: 1.0099x; 1.0099x over previous
.LBB0_22:
	v_and_or_b32 v8, v1, s27, v3
	v_ashrrev_i32_e32 v9, 31, v8
	v_lshl_add_u64 v[8:9], v[8:9], 2, s[6:7]
	global_load_dword v10, v[8:9], off offset:2048
	global_load_dword v11, v[8:9], off
	v_add_u32_e32 v6, 0x200, v6
	v_cmp_lt_i32_e32 vcc, s26, v6
	s_or_b64 s[30:31], vcc, s[30:31]
	v_add_u32_e32 v1, 0x400, v1
	s_waitcnt vmcnt(1)
	v_max_f32_e32 v8, v10, v10
	s_waitcnt vmcnt(0)
	v_max_f32_e32 v9, v11, v11
	v_max_f32_e32 v8, v9, v8
	v_sub_f32_e32 v9, v11, v8
	v_sub_f32_e32 v8, v10, v8
	v_mul_f32_e32 v10, 0x3fb8aa3b, v9
	v_mul_f32_e32 v11, 0x3fb8aa3b, v8
	v_fma_f32 v12, v9, s29, -v10
	v_rndne_f32_e32 v13, v10
	v_fma_f32 v14, v8, s29, -v11
	v_rndne_f32_e32 v15, v11
	v_fmac_f32_e32 v12, 0x32a5705f, v9
	v_sub_f32_e32 v10, v10, v13
	v_fmac_f32_e32 v14, 0x32a5705f, v8
	v_sub_f32_e32 v11, v11, v15
	v_add_f32_e32 v10, v10, v12
	v_add_f32_e32 v11, v11, v14
	v_cvt_i32_f32_e32 v13, v13
	v_cvt_i32_f32_e32 v15, v15
	v_exp_f32_e32 v10, v10
	v_exp_f32_e32 v11, v11
	v_cmp_ngt_f32_e32 vcc, s36, v8
	v_cmp_ngt_f32_e64 s[4:5], s36, v9
	v_ldexp_f32 v10, v10, v13
	v_ldexp_f32 v11, v11, v15
	v_cndmask_b32_e64 v10, 0, v10, s[4:5]
	v_cndmask_b32_e32 v11, 0, v11, vcc
	v_cmp_nlt_f32_e32 vcc, s37, v8
	v_cmp_nlt_f32_e64 s[4:5], s37, v9
	s_nop 0
	v_cndmask_b32_e32 v9, v7, v11, vcc
	v_cndmask_b32_e64 v8, v7, v10, s[4:5]
	v_add_f32_e32 v9, v8, v9
	v_div_scale_f32 v10, s[4:5], v9, v9, v8
	v_rcp_f32_e32 v11, v10
	v_div_scale_f32 v12, vcc, v8, v9, v8
	v_fma_f32 v13, -v10, v11, 1.0
	v_fmac_f32_e32 v11, v13, v11
	v_mul_f32_e32 v13, v12, v11
	v_fma_f32 v14, -v10, v13, v12
	v_fmac_f32_e32 v13, v14, v11
	v_fma_f32 v10, -v10, v13, v12
	v_div_fmas_f32 v10, v10, v11, v13
	v_div_fixup_f32 v8, v10, v9, v8
	global_store_dword v[4:5], v8, off sc1
	v_lshl_add_u64 v[4:5], v[4:5], 0, s[34:35]
	s_andn2_b64 exec, exec, s[30:31]
	s_cbranch_execnz .LBB0_22
.LBB0_23:
	s_or_b64 exec, exec, s[12:13]
	s_cmp_lt_u32 s74, 64
	s_cbranch_scc0 .LBB0_27
	v_ashrrev_i32_e32 v3, 31, v2
	v_lshlrev_b64 v[4:5], 2, v[2:3]
	v_lshl_add_u64 v[6:7], s[10:11], 0, v[4:5]
	v_lshl_add_u64 v[4:5], s[8:9], 0, v[4:5]
	global_load_dword v1, v[6:7], off
	global_load_dword v3, v[6:7], off offset:256
	global_load_dword v8, v[6:7], off offset:512
	global_load_dword v9, v[6:7], off offset:768
	s_nop 0
	global_load_dword v6, v[4:5], off
	global_load_dword v7, v[4:5], off offset:256
	v_and_b32_e32 v4, 64, v244
	v_xor_b32_e32 v5, 1, v244
	v_add_u32_e32 v4, 64, v4
	v_xor_b32_e32 v10, 2, v244
	v_cmp_lt_i32_e32 vcc, v5, v4
	v_xor_b32_e32 v11, 4, v244
	v_xor_b32_e32 v12, 8, v244
	v_cndmask_b32_e32 v5, v244, v5, vcc
	v_cmp_lt_i32_e32 vcc, v10, v4
	v_xor_b32_e32 v13, 16, v244
	v_xor_b32_e32 v14, 32, v244
	v_cndmask_b32_e32 v10, v244, v10, vcc
	v_cmp_lt_i32_e32 vcc, v11, v4
	v_lshlrev_b32_e32 v5, 2, v5
	v_lshlrev_b32_e32 v10, 2, v10
	v_cndmask_b32_e32 v11, v244, v11, vcc
	v_cmp_lt_i32_e32 vcc, v12, v4
	v_lshlrev_b32_e32 v11, 2, v11
	s_waitcnt vmcnt(1)
	v_and_b32_e32 v16, 0x7fffffff, v6
	v_cndmask_b32_e32 v12, v244, v12, vcc
	v_cmp_lt_i32_e32 vcc, v13, v4
	v_mul_f32_e32 v15, v8, v9
	s_waitcnt vmcnt(0)
	v_and_b32_e32 v17, 0x7fffffff, v7
	v_cndmask_b32_e32 v13, v244, v13, vcc
	v_cmp_lt_i32_e32 vcc, v14, v4
	ds_bpermute_b32 v15, v5, v15
	ds_bpermute_b32 v16, v5, v16
	v_cndmask_b32_e32 v4, v244, v14, vcc
	v_mul_f32_e32 v14, v1, v3
	ds_bpermute_b32 v14, v5, v14
	ds_bpermute_b32 v5, v5, v17
	v_max_f32_e64 v6, |v6|, |v6|
	v_max_f32_e64 v7, |v7|, |v7|
	s_waitcnt lgkmcnt(3)
	v_fmac_f32_e32 v15, v8, v9
	s_waitcnt lgkmcnt(1)
	v_fmac_f32_e32 v14, v1, v3
	v_max_f32_e32 v1, v16, v16
	s_waitcnt lgkmcnt(0)
	v_max_f32_e32 v3, v5, v5
	v_max_f32_e32 v1, v6, v1
	v_max_f32_e32 v3, v7, v3
	ds_bpermute_b32 v5, v10, v14
	ds_bpermute_b32 v6, v10, v15
	ds_bpermute_b32 v7, v10, v1
	ds_bpermute_b32 v8, v10, v3
	v_lshlrev_b32_e32 v9, 2, v4
	s_waitcnt lgkmcnt(3)
	v_add_f32_e32 v4, v14, v5
	s_waitcnt lgkmcnt(2)
	v_add_f32_e32 v5, v15, v6
	s_waitcnt lgkmcnt(1)
	v_max_f32_e32 v6, v7, v7
	s_waitcnt lgkmcnt(0)
	v_max_f32_e32 v7, v8, v8
	v_max_f32_e32 v1, v1, v6
	v_max_f32_e32 v3, v3, v7
	ds_bpermute_b32 v6, v11, v1
	ds_bpermute_b32 v7, v11, v3
	ds_bpermute_b32 v8, v11, v4
	ds_bpermute_b32 v10, v11, v5
	v_lshlrev_b32_e32 v12, 2, v12
	s_waitcnt lgkmcnt(3)
	v_max_f32_e32 v6, v6, v6
	s_waitcnt lgkmcnt(2)
	v_max_f32_e32 v7, v7, v7
	v_max_f32_e32 v1, v1, v6
	v_max_f32_e32 v3, v3, v7
	s_waitcnt lgkmcnt(1)
	v_add_f32_e32 v4, v4, v8
	s_waitcnt lgkmcnt(0)
	v_add_f32_e32 v5, v5, v10
	ds_bpermute_b32 v6, v12, v1
	ds_bpermute_b32 v7, v12, v3
	ds_bpermute_b32 v8, v12, v4
	ds_bpermute_b32 v10, v12, v5
	v_lshlrev_b32_e32 v13, 2, v13
	s_waitcnt lgkmcnt(3)
	v_max_f32_e32 v6, v6, v6
	s_waitcnt lgkmcnt(2)
	v_max_f32_e32 v7, v7, v7
	s_waitcnt lgkmcnt(1)
	v_add_f32_e32 v4, v4, v8
	s_waitcnt lgkmcnt(0)
	v_add_f32_e32 v8, v5, v10
	v_max_f32_e32 v11, v1, v6
	v_max_f32_e32 v7, v3, v7
	ds_bpermute_b32 v5, v13, v4
	ds_bpermute_b32 v10, v13, v8
	ds_bpermute_b32 v12, v13, v11
	ds_bpermute_b32 v13, v13, v7
	v_cmp_eq_u32_e32 vcc, 0, v2
	s_waitcnt lgkmcnt(3)
	v_add_f32_e32 v5, v4, v5
	s_waitcnt lgkmcnt(2)
	v_add_f32_e32 v1, v8, v10
	s_waitcnt lgkmcnt(1)
	v_max_f32_e32 v4, v12, v12
	s_waitcnt lgkmcnt(0)
	v_max_f32_e32 v8, v13, v13
	v_max_f32_e32 v4, v11, v4
	v_max_f32_e32 v8, v7, v8
	ds_bpermute_b32 v6, v9, v5
	ds_bpermute_b32 v3, v9, v1
	ds_bpermute_b32 v7, v9, v4
	ds_bpermute_b32 v9, v9, v8
	s_and_saveexec_b64 s[4:5], vcc
	s_cbranch_execz .LBB0_26
	s_waitcnt lgkmcnt(3)
	v_add_f32_e32 v5, v5, v6
	s_waitcnt lgkmcnt(0)
	v_max_f32_e32 v9, v9, v9
	v_max_f32_e32 v8, v8, v8
	s_mov_b32 s6, 0x3fb8aa3b
	v_mul_f32_e32 v6, 0x3fb8aa3b, v5
	v_max_f32_e32 v8, v8, v9
	v_fma_f32 v9, v5, s6, -v6
	v_rndne_f32_e32 v10, v6
	v_fmac_f32_e32 v9, 0x32a5705f, v5
	v_sub_f32_e32 v6, v6, v10
	v_add_f32_e32 v6, v6, v9
	v_exp_f32_e32 v6, v6
	v_cvt_i32_f32_e32 v9, v10
	v_max_f32_e32 v7, v7, v7
	v_max_f32_e32 v4, v4, v4
	v_add_f32_e32 v1, v1, v3
	v_max_f32_e32 v7, v4, v7
	v_mul_f32_e32 v4, 0x3fb8aa3b, v1
	v_ldexp_f32 v3, v6, v9
	v_fma_f32 v6, v1, s6, -v4
	v_rndne_f32_e32 v9, v4
	v_fmac_f32_e32 v6, 0x32a5705f, v1
	v_sub_f32_e32 v4, v4, v9
	v_add_f32_e32 v4, v4, v6
	v_exp_f32_e32 v4, v4
	v_cvt_i32_f32_e32 v6, v9
	s_mov_b32 s7, 0xc2ce8ed0
	v_cmp_ngt_f32_e32 vcc, s7, v5
	s_mov_b32 s8, 0x42b17218
	v_mov_b32_e32 v9, 0x7f800000
	v_cndmask_b32_e32 v3, 0, v3, vcc
	v_cmp_nlt_f32_e32 vcc, s8, v5
	v_ldexp_f32 v4, v4, v6
	s_nop 0
	v_cndmask_b32_e32 v3, v9, v3, vcc
	v_cmp_ngt_f32_e32 vcc, s7, v1
	s_mov_b32 s6, 0x3e4ccccd
	s_mov_b32 s7, 0x3c23d70a
	v_cndmask_b32_e32 v4, 0, v4, vcc
	v_cmp_nlt_f32_e32 vcc, s8, v1
	s_nop 1
	v_cndmask_b32_e32 v1, v9, v4, vcc
	v_sub_f32_e32 v4, v3, v1
	v_mul_f32_e32 v1, 0x41000000, v7
	v_mul_f32_e32 v1, v1, v8
	v_mul_f32_e32 v1, 0x3fb8aa3b, v1
	v_mul_f32_e32 v5, 0x3f800347, v1
	v_pk_add_f32 v[4:5], v[4:5], s[6:7]
	v_mov_b32_e32 v1, 0x139000
	global_store_dwordx2 v1, v[4:5], s[16:17] sc1

.LBB0_58:
	s_or_b64 exec, exec, s[38:39]
	v_lshl_add_u32 v1, v14, 8, 0
	s_waitcnt lgkmcnt(0)
	s_barrier
	ds_read_b128 v[110:113], v1
	ds_read_b128 v[114:117], v1 offset:16
	ds_read_b128 v[118:121], v1 offset:32
	ds_read_b128 v[122:125], v1 offset:48
	v_lshl_add_u32 v10, v109, 2, 0
	s_movk_i32 s26, 0x480
	s_waitcnt vmcnt(58) lgkmcnt(2)
	v_mul_f32_e32 v12, v49, v115
	v_mul_f32_e32 v11, v52, v111
	v_fmac_f32_e32 v11, v50, v110
	v_fmac_f32_e32 v11, v51, v112
	v_fmac_f32_e32 v12, v46, v114
	v_fmac_f32_e32 v11, v48, v113
	s_waitcnt vmcnt(57)
	v_fmac_f32_e32 v12, v47, v116
	v_add_f32_e32 v11, 0, v11
	s_waitcnt vmcnt(56)
	v_fmac_f32_e32 v12, v9, v117
	v_add_f32_e32 v11, v11, v12
	s_waitcnt vmcnt(54) lgkmcnt(1)
	v_mul_f32_e32 v12, v60, v119
	v_fmac_f32_e32 v12, v58, v118
	s_waitcnt vmcnt(53)
	v_fmac_f32_e32 v12, v59, v120
	s_waitcnt vmcnt(52)
	v_fmac_f32_e32 v12, v56, v121
	ds_read_b128 v[110:113], v1 offset:64
	ds_read_b128 v[114:117], v1 offset:80
	v_add_f32_e32 v11, v11, v12
	s_waitcnt vmcnt(50) lgkmcnt(2)
	v_mul_f32_e32 v12, v57, v123
	v_fmac_f32_e32 v12, v55, v122
	s_waitcnt vmcnt(49)
	v_fmac_f32_e32 v12, v53, v124
	s_waitcnt vmcnt(48)
	v_fmac_f32_e32 v12, v54, v125
	v_add_f32_e32 v11, v11, v12
	s_waitcnt vmcnt(46) lgkmcnt(1)
	v_mul_f32_e32 v12, v68, v111
	v_fmac_f32_e32 v12, v64, v110
	s_waitcnt vmcnt(45)
	v_fmac_f32_e32 v12, v65, v112
	s_waitcnt vmcnt(44)
	v_fmac_f32_e32 v12, v66, v113
	ds_read_b128 v[110:113], v1 offset:96
	v_add_f32_e32 v11, v11, v12
	s_waitcnt vmcnt(42) lgkmcnt(1)
	v_mul_f32_e32 v12, v67, v115
	v_fmac_f32_e32 v12, v63, v114
	s_waitcnt vmcnt(41)
	v_fmac_f32_e32 v12, v61, v116
	s_waitcnt vmcnt(40)
	v_fmac_f32_e32 v12, v62, v117
	ds_read_b128 v[114:117], v1 offset:112
	v_add_f32_e32 v11, v11, v12
	s_waitcnt vmcnt(38) lgkmcnt(1)
	v_mul_f32_e32 v12, v76, v111
	v_fmac_f32_e32 v12, v72, v110
	s_waitcnt vmcnt(37)
	v_fmac_f32_e32 v12, v73, v112
	s_waitcnt vmcnt(36)
	v_fmac_f32_e32 v12, v74, v113
	ds_read_b128 v[110:113], v1 offset:128
	v_add_f32_e32 v11, v11, v12
	s_waitcnt vmcnt(34) lgkmcnt(1)
	v_mul_f32_e32 v12, v75, v115
	v_fmac_f32_e32 v12, v71, v114
	s_waitcnt vmcnt(33)
	v_fmac_f32_e32 v12, v69, v116
	s_waitcnt vmcnt(32)
	v_fmac_f32_e32 v12, v70, v117
	ds_read_b128 v[114:117], v1 offset:144
	v_add_f32_e32 v11, v11, v12
	s_waitcnt vmcnt(30) lgkmcnt(1)
	v_mul_f32_e32 v12, v84, v111
	v_fmac_f32_e32 v12, v80, v110
	s_waitcnt vmcnt(29)
	v_fmac_f32_e32 v12, v81, v112
	s_waitcnt vmcnt(28)
	v_fmac_f32_e32 v12, v82, v113
	ds_read_b128 v[110:113], v1 offset:160
	v_add_f32_e32 v11, v11, v12
	s_waitcnt vmcnt(26) lgkmcnt(1)
	v_mul_f32_e32 v12, v83, v115
	v_fmac_f32_e32 v12, v79, v114
	s_waitcnt vmcnt(25)
	v_fmac_f32_e32 v12, v77, v116
	s_waitcnt vmcnt(24)
	v_fmac_f32_e32 v12, v78, v117
	ds_read_b128 v[114:117], v1 offset:176
	v_add_f32_e32 v11, v11, v12
	s_waitcnt vmcnt(22) lgkmcnt(1)
	v_mul_f32_e32 v12, v92, v111
	v_fmac_f32_e32 v12, v88, v110
	s_waitcnt vmcnt(21)
	v_fmac_f32_e32 v12, v89, v112
	s_waitcnt vmcnt(20)
	v_fmac_f32_e32 v12, v90, v113
	ds_read_b128 v[110:113], v1 offset:192
	v_add_f32_e32 v11, v11, v12
	s_waitcnt vmcnt(18) lgkmcnt(1)
	v_mul_f32_e32 v12, v91, v115
	v_fmac_f32_e32 v12, v87, v114
	s_waitcnt vmcnt(17)
	v_fmac_f32_e32 v12, v85, v116
	s_waitcnt vmcnt(16)
	v_fmac_f32_e32 v12, v86, v117
	ds_read_b128 v[114:117], v1 offset:208
	v_add_f32_e32 v11, v11, v12
	s_waitcnt vmcnt(14) lgkmcnt(1)
	v_mul_f32_e32 v12, v100, v111
	v_fmac_f32_e32 v12, v96, v110
	s_waitcnt vmcnt(13)
	v_fmac_f32_e32 v12, v97, v112
	s_waitcnt vmcnt(12)
	v_fmac_f32_e32 v12, v98, v113
	ds_read_b128 v[110:113], v1 offset:224
	v_add_f32_e32 v11, v11, v12
	s_waitcnt vmcnt(10) lgkmcnt(1)
	v_mul_f32_e32 v12, v99, v115
	v_fmac_f32_e32 v12, v95, v114
	s_waitcnt vmcnt(9)
	v_fmac_f32_e32 v12, v93, v116
	s_waitcnt vmcnt(8)
	v_fmac_f32_e32 v12, v94, v117
	ds_read_b128 v[114:117], v1 offset:240
	v_add_f32_e32 v11, v11, v12
	s_waitcnt vmcnt(6) lgkmcnt(1)
	v_mul_f32_e32 v12, v108, v111
	v_fmac_f32_e32 v12, v104, v110
	s_waitcnt vmcnt(5)
	v_fmac_f32_e32 v12, v105, v112
	s_waitcnt vmcnt(4)
	v_fmac_f32_e32 v12, v106, v113
	v_add_f32_e32 v11, v11, v12
	s_waitcnt vmcnt(2) lgkmcnt(0)
	v_mul_f32_e32 v12, v107, v115
	v_fmac_f32_e32 v12, v102, v114
	s_waitcnt vmcnt(1)
	v_fmac_f32_e32 v12, v103, v116
	s_waitcnt vmcnt(0)
	v_fmac_f32_e32 v12, v101, v117
	v_add_f32_e32 v11, v11, v12
	v_mad_u64_u32 v[12:13], s[26:27], v14, s26, v[10:11]
	ds_write_b32 v12, v11 offset:36864
	ds_read_b128 v[110:113], v1 offset:4096
	ds_read_b128 v[114:117], v1 offset:4112
	ds_read_b128 v[118:121], v1 offset:4128
	ds_read_b128 v[122:125], v1 offset:4144
	s_movk_i32 s26, 0x120
	s_waitcnt lgkmcnt(3)
	v_mul_f32_e32 v11, v52, v111
	v_fmac_f32_e32 v11, v50, v110
	s_waitcnt lgkmcnt(2)
	v_mul_f32_e32 v13, v49, v115
	v_fmac_f32_e32 v11, v51, v112
	v_fmac_f32_e32 v13, v46, v114
	v_fmac_f32_e32 v11, v48, v113
	v_fmac_f32_e32 v13, v47, v116
	v_add_f32_e32 v11, 0, v11
	v_fmac_f32_e32 v13, v9, v117
	v_add_f32_e32 v11, v11, v13
	s_waitcnt lgkmcnt(1)
	v_mul_f32_e32 v13, v60, v119
	v_fmac_f32_e32 v13, v58, v118
	v_fmac_f32_e32 v13, v59, v120
	v_fmac_f32_e32 v13, v56, v121
	ds_read_b128 v[110:113], v1 offset:4160
	ds_read_b128 v[114:117], v1 offset:4176
	v_add_f32_e32 v11, v11, v13
	s_waitcnt lgkmcnt(2)
	v_mul_f32_e32 v13, v57, v123
	v_fmac_f32_e32 v13, v55, v122
	v_fmac_f32_e32 v13, v53, v124
	v_fmac_f32_e32 v13, v54, v125
	v_add_f32_e32 v11, v11, v13
	s_waitcnt lgkmcnt(1)
	v_mul_f32_e32 v13, v68, v111
	v_fmac_f32_e32 v13, v64, v110
	v_fmac_f32_e32 v13, v65, v112
	v_fmac_f32_e32 v13, v66, v113
	ds_read_b128 v[110:113], v1 offset:4192
	v_add_f32_e32 v11, v11, v13
	s_waitcnt lgkmcnt(1)
	v_mul_f32_e32 v13, v67, v115
	v_fmac_f32_e32 v13, v63, v114
	v_fmac_f32_e32 v13, v61, v116
	v_fmac_f32_e32 v13, v62, v117
	ds_read_b128 v[114:117], v1 offset:4208
	v_add_f32_e32 v11, v11, v13
	s_waitcnt lgkmcnt(1)
	v_mul_f32_e32 v13, v76, v111
	v_fmac_f32_e32 v13, v72, v110
	v_fmac_f32_e32 v13, v73, v112
	v_fmac_f32_e32 v13, v74, v113
	ds_read_b128 v[110:113], v1 offset:4224
	v_add_f32_e32 v11, v11, v13
	s_waitcnt lgkmcnt(1)
	v_mul_f32_e32 v13, v75, v115
	v_fmac_f32_e32 v13, v71, v114
	v_fmac_f32_e32 v13, v69, v116
	v_fmac_f32_e32 v13, v70, v117
	ds_read_b128 v[114:117], v1 offset:4240
	v_add_f32_e32 v11, v11, v13
	s_waitcnt lgkmcnt(1)
	v_mul_f32_e32 v13, v84, v111
	v_fmac_f32_e32 v13, v80, v110
	v_fmac_f32_e32 v13, v81, v112
	v_fmac_f32_e32 v13, v82, v113
	ds_read_b128 v[110:113], v1 offset:4256
	v_add_f32_e32 v11, v11, v13
	s_waitcnt lgkmcnt(1)
	v_mul_f32_e32 v13, v83, v115
	v_fmac_f32_e32 v13, v79, v114
	v_fmac_f32_e32 v13, v77, v116
	v_fmac_f32_e32 v13, v78, v117
	ds_read_b128 v[114:117], v1 offset:4272
	v_add_f32_e32 v11, v11, v13
	s_waitcnt lgkmcnt(1)
	v_mul_f32_e32 v13, v92, v111
	v_fmac_f32_e32 v13, v88, v110
	v_fmac_f32_e32 v13, v89, v112
	v_fmac_f32_e32 v13, v90, v113
	ds_read_b128 v[110:113], v1 offset:4288
	v_add_f32_e32 v11, v11, v13
	s_waitcnt lgkmcnt(1)
	v_mul_f32_e32 v13, v91, v115
	v_fmac_f32_e32 v13, v87, v114
	v_fmac_f32_e32 v13, v85, v116
	v_fmac_f32_e32 v13, v86, v117
	ds_read_b128 v[114:117], v1 offset:4304
	v_add_f32_e32 v11, v11, v13
	s_waitcnt lgkmcnt(1)
	v_mul_f32_e32 v13, v100, v111
	v_fmac_f32_e32 v13, v96, v110
	v_fmac_f32_e32 v13, v97, v112
	v_fmac_f32_e32 v13, v98, v113
	ds_read_b128 v[110:113], v1 offset:4320
	v_add_f32_e32 v11, v11, v13
	s_waitcnt lgkmcnt(1)
	v_mul_f32_e32 v13, v99, v115
	v_fmac_f32_e32 v13, v95, v114
	v_fmac_f32_e32 v13, v93, v116
	v_fmac_f32_e32 v13, v94, v117
	ds_read_b128 v[114:117], v1 offset:4336
	v_add_f32_e32 v11, v11, v13
	s_waitcnt lgkmcnt(1)
	v_mul_f32_e32 v13, v108, v111
	v_fmac_f32_e32 v13, v104, v110
	v_fmac_f32_e32 v13, v105, v112
	v_fmac_f32_e32 v13, v106, v113
	v_add_f32_e32 v11, v11, v13
	s_waitcnt lgkmcnt(0)
	v_mul_f32_e32 v13, v107, v115
	v_fmac_f32_e32 v13, v102, v114
	v_fmac_f32_e32 v13, v103, v116
	v_fmac_f32_e32 v13, v101, v117
	v_add_f32_e32 v11, v11, v13
	ds_write_b32 v12, v11 offset:36992
	ds_read_b128 v[110:113], v1 offset:8192
	ds_read_b128 v[114:117], v1 offset:8208
	ds_read_b128 v[118:121], v1 offset:8224
	ds_read_b128 v[122:125], v1 offset:8240
	v_cmp_gt_i32_e32 vcc, s26, v0
	s_waitcnt lgkmcnt(3)
	v_mul_f32_e32 v11, v52, v111
	v_fmac_f32_e32 v11, v50, v110
	s_waitcnt lgkmcnt(2)
	v_mul_f32_e32 v13, v49, v115
	v_fmac_f32_e32 v11, v51, v112
	v_fmac_f32_e32 v13, v46, v114
	v_fmac_f32_e32 v11, v48, v113
	v_fmac_f32_e32 v13, v47, v116
	v_add_f32_e32 v11, 0, v11
	v_fmac_f32_e32 v13, v9, v117
	v_add_f32_e32 v11, v11, v13
	s_waitcnt lgkmcnt(1)
	v_mul_f32_e32 v13, v60, v119
	v_fmac_f32_e32 v13, v58, v118
	v_fmac_f32_e32 v13, v59, v120
	v_fmac_f32_e32 v13, v56, v121
	ds_read_b128 v[110:113], v1 offset:8256
	ds_read_b128 v[114:117], v1 offset:8272
	v_add_f32_e32 v11, v11, v13
	s_waitcnt lgkmcnt(2)
	v_mul_f32_e32 v13, v57, v123
	v_fmac_f32_e32 v13, v55, v122
	v_fmac_f32_e32 v13, v53, v124
	v_fmac_f32_e32 v13, v54, v125
	v_add_f32_e32 v11, v11, v13
	s_waitcnt lgkmcnt(1)
	v_mul_f32_e32 v13, v68, v111
	v_fmac_f32_e32 v13, v64, v110
	v_fmac_f32_e32 v13, v65, v112
	v_fmac_f32_e32 v13, v66, v113
	ds_read_b128 v[110:113], v1 offset:8288
	v_add_f32_e32 v11, v11, v13
	s_waitcnt lgkmcnt(1)
	v_mul_f32_e32 v13, v67, v115
	v_fmac_f32_e32 v13, v63, v114
	v_fmac_f32_e32 v13, v61, v116
	v_fmac_f32_e32 v13, v62, v117
	ds_read_b128 v[114:117], v1 offset:8304
	v_add_f32_e32 v11, v11, v13
	s_waitcnt lgkmcnt(1)
	v_mul_f32_e32 v13, v76, v111
	v_fmac_f32_e32 v13, v72, v110
	v_fmac_f32_e32 v13, v73, v112
	v_fmac_f32_e32 v13, v74, v113
	ds_read_b128 v[110:113], v1 offset:8320
	v_add_f32_e32 v11, v11, v13
	s_waitcnt lgkmcnt(1)
	v_mul_f32_e32 v13, v75, v115
	v_fmac_f32_e32 v13, v71, v114
	v_fmac_f32_e32 v13, v69, v116
	v_fmac_f32_e32 v13, v70, v117
	ds_read_b128 v[114:117], v1 offset:8336
	v_add_f32_e32 v11, v11, v13
	s_waitcnt lgkmcnt(1)
	v_mul_f32_e32 v13, v84, v111
	v_fmac_f32_e32 v13, v80, v110
	v_fmac_f32_e32 v13, v81, v112
	v_fmac_f32_e32 v13, v82, v113
	ds_read_b128 v[110:113], v1 offset:8352
	v_add_f32_e32 v11, v11, v13
	s_waitcnt lgkmcnt(1)
	v_mul_f32_e32 v13, v83, v115
	v_fmac_f32_e32 v13, v79, v114
	v_fmac_f32_e32 v13, v77, v116
	v_fmac_f32_e32 v13, v78, v117
	ds_read_b128 v[114:117], v1 offset:8368
	v_add_f32_e32 v11, v11, v13
	s_waitcnt lgkmcnt(1)
	v_mul_f32_e32 v13, v92, v111
	v_fmac_f32_e32 v13, v88, v110
	v_fmac_f32_e32 v13, v89, v112
	v_fmac_f32_e32 v13, v90, v113
	ds_read_b128 v[110:113], v1 offset:8384
	v_add_f32_e32 v11, v11, v13
	s_waitcnt lgkmcnt(1)
	v_mul_f32_e32 v13, v91, v115
	v_fmac_f32_e32 v13, v87, v114
	v_fmac_f32_e32 v13, v85, v116
	v_fmac_f32_e32 v13, v86, v117
	ds_read_b128 v[114:117], v1 offset:8400
	v_add_f32_e32 v11, v11, v13
	s_waitcnt lgkmcnt(1)
	v_mul_f32_e32 v13, v100, v111
	v_fmac_f32_e32 v13, v96, v110
	v_fmac_f32_e32 v13, v97, v112
	v_fmac_f32_e32 v13, v98, v113
	ds_read_b128 v[110:113], v1 offset:8416
	v_add_f32_e32 v11, v11, v13
	s_waitcnt lgkmcnt(1)
	v_mul_f32_e32 v13, v99, v115
	v_fmac_f32_e32 v13, v95, v114
	v_fmac_f32_e32 v13, v93, v116
	v_fmac_f32_e32 v13, v94, v117
	ds_read_b128 v[114:117], v1 offset:8432
	v_add_f32_e32 v11, v11, v13
	s_waitcnt lgkmcnt(1)
	v_mul_f32_e32 v13, v108, v111
	v_fmac_f32_e32 v13, v104, v110
	v_fmac_f32_e32 v13, v105, v112
	v_fmac_f32_e32 v13, v106, v113
	v_add_f32_e32 v11, v11, v13
	s_waitcnt lgkmcnt(0)
	v_mul_f32_e32 v13, v107, v115
	v_fmac_f32_e32 v13, v102, v114
	v_fmac_f32_e32 v13, v103, v116
	v_fmac_f32_e32 v13, v101, v117
	v_add_f32_e32 v11, v11, v13
	ds_write_b32 v12, v11 offset:37120
	ds_read_b128 v[110:113], v1 offset:12288
	ds_read_b128 v[114:117], v1 offset:12304
	ds_read_b128 v[118:121], v1 offset:12320
	ds_read_b128 v[122:125], v1 offset:12336
	s_waitcnt lgkmcnt(3)
	v_mul_f32_e32 v11, v52, v111
	v_fmac_f32_e32 v11, v50, v110
	s_waitcnt lgkmcnt(2)
	v_mul_f32_e32 v13, v49, v115
	v_fmac_f32_e32 v11, v51, v112
	v_fmac_f32_e32 v13, v46, v114
	v_fmac_f32_e32 v11, v48, v113
	v_fmac_f32_e32 v13, v47, v116
	v_add_f32_e32 v11, 0, v11
	v_fmac_f32_e32 v13, v9, v117
	v_add_f32_e32 v11, v11, v13
	s_waitcnt lgkmcnt(1)
	v_mul_f32_e32 v13, v60, v119
	v_fmac_f32_e32 v13, v58, v118
	v_fmac_f32_e32 v13, v59, v120
	v_fmac_f32_e32 v13, v56, v121
	ds_read_b128 v[110:113], v1 offset:12352
	ds_read_b128 v[114:117], v1 offset:12368
	v_add_f32_e32 v11, v11, v13
	s_waitcnt lgkmcnt(2)
	v_mul_f32_e32 v13, v57, v123
	v_fmac_f32_e32 v13, v55, v122
	v_fmac_f32_e32 v13, v53, v124
	v_fmac_f32_e32 v13, v54, v125
	v_add_f32_e32 v11, v11, v13
	s_waitcnt lgkmcnt(1)
	v_mul_f32_e32 v13, v68, v111
	v_fmac_f32_e32 v13, v64, v110
	v_fmac_f32_e32 v13, v65, v112
	v_fmac_f32_e32 v13, v66, v113
	ds_read_b128 v[110:113], v1 offset:12384
	v_add_f32_e32 v11, v11, v13
	s_waitcnt lgkmcnt(1)
	v_mul_f32_e32 v13, v67, v115
	v_fmac_f32_e32 v13, v63, v114
	v_fmac_f32_e32 v13, v61, v116
	v_fmac_f32_e32 v13, v62, v117
	ds_read_b128 v[114:117], v1 offset:12400
	v_add_f32_e32 v11, v11, v13
	s_waitcnt lgkmcnt(1)
	v_mul_f32_e32 v13, v76, v111
	v_fmac_f32_e32 v13, v72, v110
	v_fmac_f32_e32 v13, v73, v112
	v_fmac_f32_e32 v13, v74, v113
	ds_read_b128 v[110:113], v1 offset:12416
	v_add_f32_e32 v11, v11, v13
	s_waitcnt lgkmcnt(1)
	v_mul_f32_e32 v13, v75, v115
	v_fmac_f32_e32 v13, v71, v114
	v_fmac_f32_e32 v13, v69, v116
	v_fmac_f32_e32 v13, v70, v117
	ds_read_b128 v[114:117], v1 offset:12432
	v_add_f32_e32 v11, v11, v13
	s_waitcnt lgkmcnt(1)
	v_mul_f32_e32 v13, v84, v111
	v_fmac_f32_e32 v13, v80, v110
	v_fmac_f32_e32 v13, v81, v112
	v_fmac_f32_e32 v13, v82, v113
	ds_read_b128 v[110:113], v1 offset:12448
	v_add_f32_e32 v11, v11, v13
	s_waitcnt lgkmcnt(1)
	v_mul_f32_e32 v13, v83, v115
	v_fmac_f32_e32 v13, v79, v114
	v_fmac_f32_e32 v13, v77, v116
	v_fmac_f32_e32 v13, v78, v117
	ds_read_b128 v[114:117], v1 offset:12464
	v_add_f32_e32 v11, v11, v13
	s_waitcnt lgkmcnt(1)
	v_mul_f32_e32 v13, v92, v111
	v_fmac_f32_e32 v13, v88, v110
	v_fmac_f32_e32 v13, v89, v112
	v_fmac_f32_e32 v13, v90, v113
	ds_read_b128 v[110:113], v1 offset:12480
	v_add_f32_e32 v11, v11, v13
	s_waitcnt lgkmcnt(1)
	v_mul_f32_e32 v13, v91, v115
	v_fmac_f32_e32 v13, v87, v114
	v_fmac_f32_e32 v13, v85, v116
	v_fmac_f32_e32 v13, v86, v117
	ds_read_b128 v[114:117], v1 offset:12496
	v_add_f32_e32 v11, v11, v13
	s_waitcnt lgkmcnt(1)
	v_mul_f32_e32 v13, v100, v111
	v_fmac_f32_e32 v13, v96, v110
	v_fmac_f32_e32 v13, v97, v112
	v_fmac_f32_e32 v13, v98, v113
	ds_read_b128 v[110:113], v1 offset:12512
	v_add_f32_e32 v11, v11, v13
	s_waitcnt lgkmcnt(1)
	v_mul_f32_e32 v13, v99, v115
	v_fmac_f32_e32 v13, v95, v114
	v_fmac_f32_e32 v13, v93, v116
	v_fmac_f32_e32 v13, v94, v117
	ds_read_b128 v[114:117], v1 offset:12528
	v_add_f32_e32 v11, v11, v13
	s_waitcnt lgkmcnt(1)
	v_mul_f32_e32 v13, v108, v111
	v_fmac_f32_e32 v13, v104, v110
	v_fmac_f32_e32 v13, v105, v112
	v_fmac_f32_e32 v13, v106, v113
	v_add_f32_e32 v11, v11, v13
	s_waitcnt lgkmcnt(0)
	v_mul_f32_e32 v13, v107, v115
	v_fmac_f32_e32 v13, v102, v114
	v_fmac_f32_e32 v13, v103, v116
	v_fmac_f32_e32 v13, v101, v117
	v_add_f32_e32 v11, v11, v13
	ds_write_b32 v12, v11 offset:37248
	ds_read_b128 v[110:113], v1 offset:16384
	ds_read_b128 v[114:117], v1 offset:16400
	ds_read_b128 v[118:121], v1 offset:16416
	ds_read_b128 v[122:125], v1 offset:16432
	s_waitcnt lgkmcnt(3)
	v_mul_f32_e32 v11, v52, v111
	v_fmac_f32_e32 v11, v50, v110
	s_waitcnt lgkmcnt(2)
	v_mul_f32_e32 v13, v49, v115
	v_fmac_f32_e32 v11, v51, v112
	v_fmac_f32_e32 v13, v46, v114
	v_fmac_f32_e32 v11, v48, v113
	v_fmac_f32_e32 v13, v47, v116
	v_add_f32_e32 v11, 0, v11
	v_fmac_f32_e32 v13, v9, v117
	v_add_f32_e32 v11, v11, v13
	s_waitcnt lgkmcnt(1)
	v_mul_f32_e32 v13, v60, v119
	v_fmac_f32_e32 v13, v58, v118
	v_fmac_f32_e32 v13, v59, v120
	v_fmac_f32_e32 v13, v56, v121
	ds_read_b128 v[110:113], v1 offset:16448
	ds_read_b128 v[114:117], v1 offset:16464
	v_add_f32_e32 v11, v11, v13
	s_waitcnt lgkmcnt(2)
	v_mul_f32_e32 v13, v57, v123
	v_fmac_f32_e32 v13, v55, v122
	v_fmac_f32_e32 v13, v53, v124
	v_fmac_f32_e32 v13, v54, v125
	v_add_f32_e32 v11, v11, v13
	s_waitcnt lgkmcnt(1)
	v_mul_f32_e32 v13, v68, v111
	v_fmac_f32_e32 v13, v64, v110
	v_fmac_f32_e32 v13, v65, v112
	v_fmac_f32_e32 v13, v66, v113
	ds_read_b128 v[110:113], v1 offset:16480
	v_add_f32_e32 v11, v11, v13
	s_waitcnt lgkmcnt(1)
	v_mul_f32_e32 v13, v67, v115
	v_fmac_f32_e32 v13, v63, v114
	v_fmac_f32_e32 v13, v61, v116
	v_fmac_f32_e32 v13, v62, v117
	ds_read_b128 v[114:117], v1 offset:16496
	v_add_f32_e32 v11, v11, v13
	s_waitcnt lgkmcnt(1)
	v_mul_f32_e32 v13, v76, v111
	v_fmac_f32_e32 v13, v72, v110
	v_fmac_f32_e32 v13, v73, v112
	v_fmac_f32_e32 v13, v74, v113
	ds_read_b128 v[110:113], v1 offset:16512
	v_add_f32_e32 v11, v11, v13
	s_waitcnt lgkmcnt(1)
	v_mul_f32_e32 v13, v75, v115
	v_fmac_f32_e32 v13, v71, v114
	v_fmac_f32_e32 v13, v69, v116
	v_fmac_f32_e32 v13, v70, v117
	ds_read_b128 v[114:117], v1 offset:16528
	v_add_f32_e32 v11, v11, v13
	s_waitcnt lgkmcnt(1)
	v_mul_f32_e32 v13, v84, v111
	v_fmac_f32_e32 v13, v80, v110
	v_fmac_f32_e32 v13, v81, v112
	v_fmac_f32_e32 v13, v82, v113
	ds_read_b128 v[110:113], v1 offset:16544
	v_add_f32_e32 v11, v11, v13
	s_waitcnt lgkmcnt(1)
	v_mul_f32_e32 v13, v83, v115
	v_fmac_f32_e32 v13, v79, v114
	v_fmac_f32_e32 v13, v77, v116
	v_fmac_f32_e32 v13, v78, v117
	ds_read_b128 v[114:117], v1 offset:16560
	v_add_f32_e32 v11, v11, v13
	s_waitcnt lgkmcnt(1)
	v_mul_f32_e32 v13, v92, v111
	v_fmac_f32_e32 v13, v88, v110
	v_fmac_f32_e32 v13, v89, v112
	v_fmac_f32_e32 v13, v90, v113
	ds_read_b128 v[110:113], v1 offset:16576
	v_add_f32_e32 v11, v11, v13
	s_waitcnt lgkmcnt(1)
	v_mul_f32_e32 v13, v91, v115
	v_fmac_f32_e32 v13, v87, v114
	v_fmac_f32_e32 v13, v85, v116
	v_fmac_f32_e32 v13, v86, v117
	ds_read_b128 v[114:117], v1 offset:16592
	v_add_f32_e32 v11, v11, v13
	s_waitcnt lgkmcnt(1)
	v_mul_f32_e32 v13, v100, v111
	v_fmac_f32_e32 v13, v96, v110
	v_fmac_f32_e32 v13, v97, v112
	v_fmac_f32_e32 v13, v98, v113
	ds_read_b128 v[110:113], v1 offset:16608
	v_add_f32_e32 v11, v11, v13
	s_waitcnt lgkmcnt(1)
	v_mul_f32_e32 v13, v99, v115
	v_fmac_f32_e32 v13, v95, v114
	v_fmac_f32_e32 v13, v93, v116
	v_fmac_f32_e32 v13, v94, v117
	ds_read_b128 v[114:117], v1 offset:16624
	v_add_f32_e32 v11, v11, v13
	s_waitcnt lgkmcnt(1)
	v_mul_f32_e32 v13, v108, v111
	v_fmac_f32_e32 v13, v104, v110
	v_fmac_f32_e32 v13, v105, v112
	v_fmac_f32_e32 v13, v106, v113
	v_add_f32_e32 v11, v11, v13
	s_waitcnt lgkmcnt(0)
	v_mul_f32_e32 v13, v107, v115
	v_fmac_f32_e32 v13, v102, v114
	v_fmac_f32_e32 v13, v103, v116
	v_fmac_f32_e32 v13, v101, v117
	v_add_f32_e32 v11, v11, v13
	ds_write_b32 v12, v11 offset:37376
	ds_read_b128 v[110:113], v1 offset:20480
	ds_read_b128 v[114:117], v1 offset:20496
	ds_read_b128 v[118:121], v1 offset:20512
	ds_read_b128 v[122:125], v1 offset:20528
	s_waitcnt lgkmcnt(3)
	v_mul_f32_e32 v11, v52, v111
	v_fmac_f32_e32 v11, v50, v110
	s_waitcnt lgkmcnt(2)
	v_mul_f32_e32 v13, v49, v115
	v_fmac_f32_e32 v11, v51, v112
	v_fmac_f32_e32 v13, v46, v114
	v_fmac_f32_e32 v11, v48, v113
	v_fmac_f32_e32 v13, v47, v116
	v_add_f32_e32 v11, 0, v11
	v_fmac_f32_e32 v13, v9, v117
	v_add_f32_e32 v11, v11, v13
	s_waitcnt lgkmcnt(1)
	v_mul_f32_e32 v13, v60, v119
	v_fmac_f32_e32 v13, v58, v118
	v_fmac_f32_e32 v13, v59, v120
	v_fmac_f32_e32 v13, v56, v121
	ds_read_b128 v[110:113], v1 offset:20544
	ds_read_b128 v[114:117], v1 offset:20560
	v_add_f32_e32 v11, v11, v13
	s_waitcnt lgkmcnt(2)
	v_mul_f32_e32 v13, v57, v123
	v_fmac_f32_e32 v13, v55, v122
	v_fmac_f32_e32 v13, v53, v124
	v_fmac_f32_e32 v13, v54, v125
	v_add_f32_e32 v11, v11, v13
	s_waitcnt lgkmcnt(1)
	v_mul_f32_e32 v13, v68, v111
	v_fmac_f32_e32 v13, v64, v110
	v_fmac_f32_e32 v13, v65, v112
	v_fmac_f32_e32 v13, v66, v113
	ds_read_b128 v[110:113], v1 offset:20576
	v_add_f32_e32 v11, v11, v13
	s_waitcnt lgkmcnt(1)
	v_mul_f32_e32 v13, v67, v115
	v_fmac_f32_e32 v13, v63, v114
	v_fmac_f32_e32 v13, v61, v116
	v_fmac_f32_e32 v13, v62, v117
	ds_read_b128 v[114:117], v1 offset:20592
	v_add_f32_e32 v11, v11, v13
	s_waitcnt lgkmcnt(1)
	v_mul_f32_e32 v13, v76, v111
	v_fmac_f32_e32 v13, v72, v110
	v_fmac_f32_e32 v13, v73, v112
	v_fmac_f32_e32 v13, v74, v113
	ds_read_b128 v[110:113], v1 offset:20608
	v_add_f32_e32 v11, v11, v13
	s_waitcnt lgkmcnt(1)
	v_mul_f32_e32 v13, v75, v115
	v_fmac_f32_e32 v13, v71, v114
	v_fmac_f32_e32 v13, v69, v116
	v_fmac_f32_e32 v13, v70, v117
	ds_read_b128 v[114:117], v1 offset:20624
	v_add_f32_e32 v11, v11, v13
	s_waitcnt lgkmcnt(1)
	v_mul_f32_e32 v13, v84, v111
	v_fmac_f32_e32 v13, v80, v110
	v_fmac_f32_e32 v13, v81, v112
	v_fmac_f32_e32 v13, v82, v113
	ds_read_b128 v[110:113], v1 offset:20640
	v_add_f32_e32 v11, v11, v13
	s_waitcnt lgkmcnt(1)
	v_mul_f32_e32 v13, v83, v115
	v_fmac_f32_e32 v13, v79, v114
	v_fmac_f32_e32 v13, v77, v116
	v_fmac_f32_e32 v13, v78, v117
	ds_read_b128 v[114:117], v1 offset:20656
	v_add_f32_e32 v11, v11, v13
	s_waitcnt lgkmcnt(1)
	v_mul_f32_e32 v13, v92, v111
	v_fmac_f32_e32 v13, v88, v110
	v_fmac_f32_e32 v13, v89, v112
	v_fmac_f32_e32 v13, v90, v113
	ds_read_b128 v[110:113], v1 offset:20672
	v_add_f32_e32 v11, v11, v13
	s_waitcnt lgkmcnt(1)
	v_mul_f32_e32 v13, v91, v115
	v_fmac_f32_e32 v13, v87, v114
	v_fmac_f32_e32 v13, v85, v116
	v_fmac_f32_e32 v13, v86, v117
	ds_read_b128 v[114:117], v1 offset:20688
	v_add_f32_e32 v11, v11, v13
	s_waitcnt lgkmcnt(1)
	v_mul_f32_e32 v13, v100, v111
	v_fmac_f32_e32 v13, v96, v110
	v_fmac_f32_e32 v13, v97, v112
	v_fmac_f32_e32 v13, v98, v113
	ds_read_b128 v[110:113], v1 offset:20704
	v_add_f32_e32 v11, v11, v13
	s_waitcnt lgkmcnt(1)
	v_mul_f32_e32 v13, v99, v115
	v_fmac_f32_e32 v13, v95, v114
	v_fmac_f32_e32 v13, v93, v116
	v_fmac_f32_e32 v13, v94, v117
	ds_read_b128 v[114:117], v1 offset:20720
	v_add_f32_e32 v11, v11, v13
	s_waitcnt lgkmcnt(1)
	v_mul_f32_e32 v13, v108, v111
	v_fmac_f32_e32 v13, v104, v110
	v_fmac_f32_e32 v13, v105, v112
	v_fmac_f32_e32 v13, v106, v113
	v_add_f32_e32 v11, v11, v13
	s_waitcnt lgkmcnt(0)
	v_mul_f32_e32 v13, v107, v115
	v_fmac_f32_e32 v13, v102, v114
	v_fmac_f32_e32 v13, v103, v116
	v_fmac_f32_e32 v13, v101, v117
	v_add_f32_e32 v11, v11, v13
	ds_write_b32 v12, v11 offset:37504
	ds_read_b128 v[110:113], v1 offset:24576
	ds_read_b128 v[114:117], v1 offset:24592
	ds_read_b128 v[118:121], v1 offset:24608
	ds_read_b128 v[122:125], v1 offset:24624
	s_waitcnt lgkmcnt(3)
	v_mul_f32_e32 v11, v52, v111
	v_fmac_f32_e32 v11, v50, v110
	s_waitcnt lgkmcnt(2)
	v_mul_f32_e32 v13, v49, v115
	v_fmac_f32_e32 v11, v51, v112
	v_fmac_f32_e32 v13, v46, v114
	v_fmac_f32_e32 v11, v48, v113
	v_fmac_f32_e32 v13, v47, v116
	v_add_f32_e32 v11, 0, v11
	v_fmac_f32_e32 v13, v9, v117
	v_add_f32_e32 v11, v11, v13
	s_waitcnt lgkmcnt(1)
	v_mul_f32_e32 v13, v60, v119
	v_fmac_f32_e32 v13, v58, v118
	v_fmac_f32_e32 v13, v59, v120
	v_fmac_f32_e32 v13, v56, v121
	ds_read_b128 v[110:113], v1 offset:24640
	ds_read_b128 v[114:117], v1 offset:24656
	v_add_f32_e32 v11, v11, v13
	s_waitcnt lgkmcnt(2)
	v_mul_f32_e32 v13, v57, v123
	v_fmac_f32_e32 v13, v55, v122
	v_fmac_f32_e32 v13, v53, v124
	v_fmac_f32_e32 v13, v54, v125
	v_add_f32_e32 v11, v11, v13
	s_waitcnt lgkmcnt(1)
	v_mul_f32_e32 v13, v68, v111
	v_fmac_f32_e32 v13, v64, v110
	v_fmac_f32_e32 v13, v65, v112
	v_fmac_f32_e32 v13, v66, v113
	ds_read_b128 v[110:113], v1 offset:24672
	v_add_f32_e32 v11, v11, v13
	s_waitcnt lgkmcnt(1)
	v_mul_f32_e32 v13, v67, v115
	v_fmac_f32_e32 v13, v63, v114
	v_fmac_f32_e32 v13, v61, v116
	v_fmac_f32_e32 v13, v62, v117
	ds_read_b128 v[114:117], v1 offset:24688
	v_add_f32_e32 v11, v11, v13
	s_waitcnt lgkmcnt(1)
	v_mul_f32_e32 v13, v76, v111
	v_fmac_f32_e32 v13, v72, v110
	v_fmac_f32_e32 v13, v73, v112
	v_fmac_f32_e32 v13, v74, v113
	ds_read_b128 v[110:113], v1 offset:24704
	v_add_f32_e32 v11, v11, v13
	s_waitcnt lgkmcnt(1)
	v_mul_f32_e32 v13, v75, v115
	v_fmac_f32_e32 v13, v71, v114
	v_fmac_f32_e32 v13, v69, v116
	v_fmac_f32_e32 v13, v70, v117
	ds_read_b128 v[114:117], v1 offset:24720
	v_add_f32_e32 v11, v11, v13
	s_waitcnt lgkmcnt(1)
	v_mul_f32_e32 v13, v84, v111
	v_fmac_f32_e32 v13, v80, v110
	v_fmac_f32_e32 v13, v81, v112
	v_fmac_f32_e32 v13, v82, v113
	ds_read_b128 v[110:113], v1 offset:24736
	v_add_f32_e32 v11, v11, v13
	s_waitcnt lgkmcnt(1)
	v_mul_f32_e32 v13, v83, v115
	v_fmac_f32_e32 v13, v79, v114
	v_fmac_f32_e32 v13, v77, v116
	v_fmac_f32_e32 v13, v78, v117
	ds_read_b128 v[114:117], v1 offset:24752
	v_add_f32_e32 v11, v11, v13
	s_waitcnt lgkmcnt(1)
	v_mul_f32_e32 v13, v92, v111
	v_fmac_f32_e32 v13, v88, v110
	v_fmac_f32_e32 v13, v89, v112
	v_fmac_f32_e32 v13, v90, v113
	ds_read_b128 v[110:113], v1 offset:24768
	v_add_f32_e32 v11, v11, v13
	s_waitcnt lgkmcnt(1)
	v_mul_f32_e32 v13, v91, v115
	v_fmac_f32_e32 v13, v87, v114
	v_fmac_f32_e32 v13, v85, v116
	v_fmac_f32_e32 v13, v86, v117
	ds_read_b128 v[114:117], v1 offset:24784
	v_add_f32_e32 v11, v11, v13
	s_waitcnt lgkmcnt(1)
	v_mul_f32_e32 v13, v100, v111
	v_fmac_f32_e32 v13, v96, v110
	v_fmac_f32_e32 v13, v97, v112
	v_fmac_f32_e32 v13, v98, v113
	ds_read_b128 v[110:113], v1 offset:24800
	v_add_f32_e32 v11, v11, v13
	s_waitcnt lgkmcnt(1)
	v_mul_f32_e32 v13, v99, v115
	v_fmac_f32_e32 v13, v95, v114
	v_fmac_f32_e32 v13, v93, v116
	v_fmac_f32_e32 v13, v94, v117
	ds_read_b128 v[114:117], v1 offset:24816
	v_add_f32_e32 v11, v11, v13
	s_waitcnt lgkmcnt(1)
	v_mul_f32_e32 v13, v108, v111
	v_fmac_f32_e32 v13, v104, v110
	v_fmac_f32_e32 v13, v105, v112
	v_fmac_f32_e32 v13, v106, v113
	v_add_f32_e32 v11, v11, v13
	s_waitcnt lgkmcnt(0)
	v_mul_f32_e32 v13, v107, v115
	v_fmac_f32_e32 v13, v102, v114
	v_fmac_f32_e32 v13, v103, v116
	v_fmac_f32_e32 v13, v101, v117
	v_add_f32_e32 v11, v11, v13
	ds_write_b32 v12, v11 offset:37632
	ds_read_b128 v[110:113], v1 offset:28672
	ds_read_b128 v[114:117], v1 offset:28688
	ds_read_b128 v[118:121], v1 offset:28704
	ds_read_b128 v[122:125], v1 offset:28720
	s_waitcnt lgkmcnt(3)
	v_mul_f32_e32 v11, v52, v111
	v_fmac_f32_e32 v11, v50, v110
	s_waitcnt lgkmcnt(2)
	v_mul_f32_e32 v13, v49, v115
	v_fmac_f32_e32 v11, v51, v112
	v_fmac_f32_e32 v13, v46, v114
	v_fmac_f32_e32 v11, v48, v113
	v_fmac_f32_e32 v13, v47, v116
	v_add_f32_e32 v11, 0, v11
	v_fmac_f32_e32 v13, v9, v117
	v_add_f32_e32 v11, v11, v13
	s_waitcnt lgkmcnt(1)
	v_mul_f32_e32 v13, v60, v119
	v_fmac_f32_e32 v13, v58, v118
	v_fmac_f32_e32 v13, v59, v120
	v_fmac_f32_e32 v13, v56, v121
	ds_read_b128 v[110:113], v1 offset:28736
	ds_read_b128 v[114:117], v1 offset:28752
	v_add_f32_e32 v11, v11, v13
	s_waitcnt lgkmcnt(2)
	v_mul_f32_e32 v13, v57, v123
	v_fmac_f32_e32 v13, v55, v122
	v_fmac_f32_e32 v13, v53, v124
	v_fmac_f32_e32 v13, v54, v125
	v_add_f32_e32 v11, v11, v13
	s_waitcnt lgkmcnt(1)
	v_mul_f32_e32 v13, v68, v111
	v_fmac_f32_e32 v13, v64, v110
	v_fmac_f32_e32 v13, v65, v112
	v_fmac_f32_e32 v13, v66, v113
	ds_read_b128 v[110:113], v1 offset:28768
	v_add_f32_e32 v11, v11, v13
	s_waitcnt lgkmcnt(1)
	v_mul_f32_e32 v13, v67, v115
	v_fmac_f32_e32 v13, v63, v114
	v_fmac_f32_e32 v13, v61, v116
	v_fmac_f32_e32 v13, v62, v117
	ds_read_b128 v[114:117], v1 offset:28784
	v_add_f32_e32 v11, v11, v13
	s_waitcnt lgkmcnt(1)
	v_mul_f32_e32 v13, v76, v111
	v_fmac_f32_e32 v13, v72, v110
	v_fmac_f32_e32 v13, v73, v112
	v_fmac_f32_e32 v13, v74, v113
	ds_read_b128 v[110:113], v1 offset:28800
	v_add_f32_e32 v11, v11, v13
	s_waitcnt lgkmcnt(1)
	v_mul_f32_e32 v13, v75, v115
	v_fmac_f32_e32 v13, v71, v114
	v_fmac_f32_e32 v13, v69, v116
	v_fmac_f32_e32 v13, v70, v117
	ds_read_b128 v[114:117], v1 offset:28816
	v_add_f32_e32 v11, v11, v13
	s_waitcnt lgkmcnt(1)
	v_mul_f32_e32 v13, v84, v111
	v_fmac_f32_e32 v13, v80, v110
	v_fmac_f32_e32 v13, v81, v112
	v_fmac_f32_e32 v13, v82, v113
	ds_read_b128 v[110:113], v1 offset:28832
	v_add_f32_e32 v11, v11, v13
	s_waitcnt lgkmcnt(1)
	v_mul_f32_e32 v13, v83, v115
	v_fmac_f32_e32 v13, v79, v114
	v_fmac_f32_e32 v13, v77, v116
	v_fmac_f32_e32 v13, v78, v117
	ds_read_b128 v[114:117], v1 offset:28848
	v_add_f32_e32 v11, v11, v13
	s_waitcnt lgkmcnt(1)
	v_mul_f32_e32 v13, v92, v111
	v_fmac_f32_e32 v13, v88, v110
	v_fmac_f32_e32 v13, v89, v112
	v_fmac_f32_e32 v13, v90, v113
	ds_read_b128 v[110:113], v1 offset:28864
	v_add_f32_e32 v11, v11, v13
	s_waitcnt lgkmcnt(1)
	v_mul_f32_e32 v13, v91, v115
	v_fmac_f32_e32 v13, v87, v114
	v_fmac_f32_e32 v13, v85, v116
	v_fmac_f32_e32 v13, v86, v117
	ds_read_b128 v[114:117], v1 offset:28880
	v_add_f32_e32 v11, v11, v13
	s_waitcnt lgkmcnt(1)
	v_mul_f32_e32 v13, v100, v111
	v_fmac_f32_e32 v13, v96, v110
	v_fmac_f32_e32 v13, v97, v112
	v_fmac_f32_e32 v13, v98, v113
	ds_read_b128 v[110:113], v1 offset:28896
	v_add_f32_e32 v11, v11, v13
	s_waitcnt lgkmcnt(1)
	v_mul_f32_e32 v13, v99, v115
	v_fmac_f32_e32 v13, v95, v114
	v_fmac_f32_e32 v13, v93, v116
	v_fmac_f32_e32 v13, v94, v117
	ds_read_b128 v[114:117], v1 offset:28912
	v_add_f32_e32 v11, v11, v13
	s_waitcnt lgkmcnt(1)
	v_mul_f32_e32 v13, v108, v111
	v_fmac_f32_e32 v13, v104, v110
	v_fmac_f32_e32 v13, v105, v112
	v_fmac_f32_e32 v13, v106, v113
	v_add_f32_e32 v11, v11, v13
	s_waitcnt lgkmcnt(0)
	v_mul_f32_e32 v13, v107, v115
	v_fmac_f32_e32 v13, v102, v114
	v_fmac_f32_e32 v13, v103, v116
	v_fmac_f32_e32 v13, v101, v117
	v_add_f32_e32 v11, v11, v13
	ds_write_b32 v12, v11 offset:37760
	ds_read_b128 v[110:113], v1 offset:32768
	ds_read_b128 v[114:117], v1 offset:32784
	ds_read_b128 v[118:121], v1 offset:32800
	ds_read_b128 v[122:125], v1 offset:32816
	s_waitcnt lgkmcnt(3)
	v_mul_f32_e32 v11, v52, v111
	v_fmac_f32_e32 v11, v50, v110
	s_waitcnt lgkmcnt(2)
	v_mul_f32_e32 v13, v49, v115
	v_fmac_f32_e32 v11, v51, v112
	v_fmac_f32_e32 v13, v46, v114
	v_fmac_f32_e32 v11, v48, v113
	v_fmac_f32_e32 v13, v47, v116
	v_add_f32_e32 v11, 0, v11
	v_fmac_f32_e32 v13, v9, v117
	v_add_f32_e32 v9, v11, v13
	s_waitcnt lgkmcnt(1)
	v_mul_f32_e32 v11, v60, v119
	v_fmac_f32_e32 v11, v58, v118
	v_fmac_f32_e32 v11, v59, v120
	v_fmac_f32_e32 v11, v56, v121
	ds_read_b128 v[46:49], v1 offset:32832
	v_add_f32_e32 v9, v9, v11
	s_waitcnt lgkmcnt(1)
	v_mul_f32_e32 v11, v57, v123
	v_fmac_f32_e32 v11, v55, v122
	v_fmac_f32_e32 v11, v53, v124
	v_fmac_f32_e32 v11, v54, v125
	ds_read_b128 v[50:53], v1 offset:32848
	v_add_f32_e32 v9, v9, v11
	s_waitcnt lgkmcnt(1)
	v_mul_f32_e32 v11, v68, v47
	v_fmac_f32_e32 v11, v64, v46
	v_fmac_f32_e32 v11, v65, v48
	v_fmac_f32_e32 v11, v66, v49
	ds_read_b128 v[46:49], v1 offset:32864
	v_add_f32_e32 v9, v9, v11
	s_waitcnt lgkmcnt(1)
	v_mul_f32_e32 v11, v67, v51
	v_fmac_f32_e32 v11, v63, v50
	v_fmac_f32_e32 v11, v61, v52
	v_fmac_f32_e32 v11, v62, v53
	ds_read_b128 v[50:53], v1 offset:32880
	v_add_f32_e32 v9, v9, v11
	s_waitcnt lgkmcnt(1)
	v_mul_f32_e32 v11, v76, v47
	v_fmac_f32_e32 v11, v72, v46
	v_fmac_f32_e32 v11, v73, v48
	v_fmac_f32_e32 v11, v74, v49
	ds_read_b128 v[46:49], v1 offset:32896
	v_add_f32_e32 v9, v9, v11
	s_waitcnt lgkmcnt(1)
	v_mul_f32_e32 v11, v75, v51
	v_fmac_f32_e32 v11, v71, v50
	v_fmac_f32_e32 v11, v69, v52
	v_fmac_f32_e32 v11, v70, v53
	ds_read_b128 v[50:53], v1 offset:32912
	v_add_f32_e32 v9, v9, v11
	s_waitcnt lgkmcnt(1)
	v_mul_f32_e32 v11, v84, v47
	v_fmac_f32_e32 v11, v80, v46
	v_fmac_f32_e32 v11, v81, v48
	v_fmac_f32_e32 v11, v82, v49
	ds_read_b128 v[46:49], v1 offset:32928
	v_add_f32_e32 v9, v9, v11
	s_waitcnt lgkmcnt(1)
	v_mul_f32_e32 v11, v83, v51
	v_fmac_f32_e32 v11, v79, v50
	v_fmac_f32_e32 v11, v77, v52
	v_fmac_f32_e32 v11, v78, v53
	ds_read_b128 v[50:53], v1 offset:32944
	v_add_f32_e32 v9, v9, v11
	s_waitcnt lgkmcnt(1)
	v_mul_f32_e32 v11, v92, v47
	v_fmac_f32_e32 v11, v88, v46
	v_fmac_f32_e32 v11, v89, v48
	v_fmac_f32_e32 v11, v90, v49
	ds_read_b128 v[46:49], v1 offset:32960
	v_add_f32_e32 v9, v9, v11
	s_waitcnt lgkmcnt(1)
	v_mul_f32_e32 v11, v91, v51
	v_fmac_f32_e32 v11, v87, v50
	v_fmac_f32_e32 v11, v85, v52
	v_fmac_f32_e32 v11, v86, v53
	ds_read_b128 v[50:53], v1 offset:32976
	v_add_f32_e32 v9, v9, v11
	s_waitcnt lgkmcnt(1)
	v_mul_f32_e32 v11, v100, v47
	v_fmac_f32_e32 v11, v96, v46
	v_fmac_f32_e32 v11, v97, v48
	v_fmac_f32_e32 v11, v98, v49
	ds_read_b128 v[46:49], v1 offset:32992
	v_add_f32_e32 v9, v9, v11
	s_waitcnt lgkmcnt(1)
	v_mul_f32_e32 v11, v99, v51
	v_fmac_f32_e32 v11, v95, v50
	v_fmac_f32_e32 v11, v93, v52
	v_fmac_f32_e32 v11, v94, v53
	ds_read_b128 v[50:53], v1 offset:33008
	s_waitcnt lgkmcnt(1)
	v_mul_f32_e32 v1, v108, v47
	v_fmac_f32_e32 v1, v104, v46
	v_fmac_f32_e32 v1, v105, v48
	v_add_f32_e32 v9, v9, v11
	v_fmac_f32_e32 v1, v106, v49
	v_add_f32_e32 v1, v9, v1
	s_waitcnt lgkmcnt(0)
	v_mul_f32_e32 v9, v107, v51
	v_fmac_f32_e32 v9, v102, v50
	v_fmac_f32_e32 v9, v103, v52
	v_fmac_f32_e32 v9, v101, v53
	v_add_f32_e32 v1, v1, v9
	ds_write_b32 v12, v1 offset:37888
	s_waitcnt lgkmcnt(0)
	s_barrier
	s_and_saveexec_b64 s[34:35], vcc
	s_cbranch_execz .LBB0_60
	v_mov_b32_e32 v12, s12
	v_mov_b32_e32 v13, s13
	v_ashrrev_i32_e32 v9, 31, v8
	v_lshl_add_u64 v[8:9], v[8:9], 2, v[12:13]
	global_load_dword v1, v[8:9], off
	v_lshl_add_u32 v8, v14, 7, v10
	v_mad_i32_i24 v9, v15, 9, v14
	ds_read_b32 v10, v8 offset:36864
	ds_read_b32 v11, v8 offset:38016
	ds_read_b32 v12, v8 offset:39168
	ds_read_b32 v13, v8 offset:40320
	ds_read_b32 v14, v8 offset:41472
	ds_read_b32 v15, v8 offset:42624
	ds_read_b32 v46, v8 offset:43776
	ds_read_b32 v47, v8 offset:44928
	ds_read_b32 v48, v8 offset:46080
	ds_read_b32 v49, v8 offset:47232
	ds_read_b32 v50, v8 offset:48384
	ds_read_b32 v51, v8 offset:49536
	ds_read_b32 v52, v8 offset:50688
	ds_read_b32 v53, v8 offset:51840
	ds_read_b32 v54, v8 offset:52992
	ds_read_b32 v55, v8 offset:54144
	s_movk_i32 s12, 0xc00
	v_mad_u64_u32 v[8:9], s[12:13], v9, s12, v[6:7]
	v_ashrrev_i32_e32 v9, 31, v8
	v_lshl_add_u64 v[8:9], v[8:9], 2, s[16:17]
	v_add_co_u32_e32 v8, vcc, 0x100000, v8
	s_waitcnt vmcnt(0) lgkmcnt(14)
	v_add_f32_e32 v1, v1, v10
	v_add_f32_e32 v1, v1, v11
	s_waitcnt lgkmcnt(13)
	v_add_f32_e32 v1, v1, v12
	s_waitcnt lgkmcnt(12)
	v_add_f32_e32 v1, v1, v13
	s_waitcnt lgkmcnt(11)
	v_add_f32_e32 v1, v1, v14
	s_waitcnt lgkmcnt(10)
	v_add_f32_e32 v1, v1, v15
	s_waitcnt lgkmcnt(9)
	v_add_f32_e32 v1, v1, v46
	s_waitcnt lgkmcnt(8)
	v_add_f32_e32 v1, v1, v47
	s_waitcnt lgkmcnt(7)
	v_add_f32_e32 v1, v1, v48
	s_waitcnt lgkmcnt(6)
	v_add_f32_e32 v1, v1, v49
	s_waitcnt lgkmcnt(5)
	v_add_f32_e32 v1, v1, v50
	s_waitcnt lgkmcnt(4)
	v_add_f32_e32 v1, v1, v51
	s_waitcnt lgkmcnt(3)
	v_add_f32_e32 v1, v1, v52
	s_waitcnt lgkmcnt(2)
	v_add_f32_e32 v1, v1, v53
	s_waitcnt lgkmcnt(1)
	v_add_f32_e32 v1, v1, v54
	s_waitcnt lgkmcnt(0)
	v_add_f32_e32 v1, v1, v55
	v_addc_co_u32_e32 v9, vcc, 0, v9, vcc
	global_store_dword v[8:9], v1, off sc1
.LBB0_60:
	s_or_b64 exec, exec, s[34:35]
	s_mov_b32 s12, 0x200000
	s_and_b64 s[4:5], s[4:5], exec
	s_cselect_b32 s4, s12, 0xb00000
	s_add_u32 s12, s16, s4
	s_movk_i32 s4, 0x84
	v_mul_lo_u32 v1, v3, s4
	v_add3_u32 v1, s28, v4, v1
	v_add_u32_e32 v3, 0x400, v1
	s_barrier
	ds_write2_b32 v1, v5, v7 offset1:66
	ds_write2_b32 v1, v16, v18 offset0:132 offset1:198
	ds_write2_b32 v3, v17, v19 offset0:8 offset1:74
	ds_write2_b32 v3, v20, v21 offset0:140 offset1:206
	v_add_u32_e32 v3, 0x800, v1
	ds_write2_b32 v3, v22, v23 offset0:16 offset1:82
	ds_write2_b32 v3, v24, v26 offset0:148 offset1:214
	v_add_u32_e32 v3, 0xc00, v1
	ds_write2_b32 v3, v25, v27 offset0:24 offset1:90
	ds_write2_b32 v3, v28, v29 offset0:156 offset1:222
	v_add_u32_e32 v3, 0x1000, v1
	ds_write2_b32 v3, v30, v31 offset0:32 offset1:98
	ds_write2_b32 v3, v32, v34 offset0:164 offset1:230
	v_add_u32_e32 v3, 0x1400, v1
	ds_write2_b32 v3, v33, v35 offset0:40 offset1:106
	ds_write2_b32 v3, v36, v37 offset0:172 offset1:238
	v_add_u32_e32 v3, 0x1800, v1
	ds_write2_b32 v3, v38, v39 offset0:48 offset1:114
	ds_write2_b32 v3, v40, v42 offset0:180 offset1:246
	v_add_u32_e32 v1, 0x1c00, v1
	v_lshlrev_b32_e32 v3, 3, v2
	ds_write2_b32 v1, v41, v43 offset0:56 offset1:122
	ds_write2_b32 v1, v44, v45 offset0:188 offset1:254
	v_ashrrev_i32_e32 v1, 3, v2
	v_and_b32_e32 v3, 56, v3
	s_waitcnt lgkmcnt(0)
	v_mul_u32_u24_e32 v6, 0x84, v3
	v_lshlrev_b32_e32 v4, 1, v3
	v_lshlrev_b32_e32 v3, 2, v1
	v_add3_u32 v3, s28, v6, v3
	s_addc_u32 s13, s17, 0
	s_ashr_i32 s31, s30, 31
	ds_read2_b32 v[8:9], v3 offset0:33 offset1:41
	ds_read2_b32 v[10:11], v3 offset1:8
	ds_read2_b32 v[12:13], v3 offset0:66 offset1:74
	ds_read2_b32 v[14:15], v3 offset0:99 offset1:107
	ds_read2_b32 v[16:17], v3 offset0:132 offset1:140
	ds_read2_b32 v[18:19], v3 offset0:165 offset1:173
	ds_read2_b32 v[20:21], v3 offset0:198 offset1:206
	ds_read2_b32 v[22:23], v3 offset0:231 offset1:239
	s_lshl_b64 s[4:5], s[30:31], 1
	s_add_u32 s4, s12, s4
	v_add_u32_e32 v26, s29, v1
	s_addc_u32 s5, s13, s5
	v_mov_b32_e32 v5, 0
	v_ashrrev_i32_e32 v27, 31, v26
	v_lshl_add_u64 v[24:25], s[4:5], 0, v[4:5]
	v_lshlrev_b64 v[28:29], 11, v[26:27]
	s_waitcnt lgkmcnt(6)
	v_cvt_pk_bf16_f32 v4, v10, v8
	s_waitcnt lgkmcnt(4)
	v_cvt_pk_bf16_f32 v5, v12, v14
	s_waitcnt lgkmcnt(2)
	v_cvt_pk_bf16_f32 v6, v16, v18
	s_waitcnt lgkmcnt(0)
	v_cvt_pk_bf16_f32 v7, v20, v22
	v_lshl_add_u64 v[28:29], v[24:25], 0, v[28:29]
	v_add_u32_e32 v8, 8, v26
	global_store_dwordx4 v[28:29], v[4:7], off sc1
	v_cmp_eq_u32_e32 vcc, 0, v0
	s_nop 0
	v_cvt_pk_bf16_f32 v4, v11, v9
	v_ashrrev_i32_e32 v9, 31, v8
	v_cvt_pk_bf16_f32 v5, v13, v15
	v_cvt_pk_bf16_f32 v6, v17, v19
	v_cvt_pk_bf16_f32 v7, v21, v23
	v_lshlrev_b64 v[8:9], 11, v[8:9]
	ds_read2_b32 v[10:11], v3 offset0:49 offset1:57
	ds_read2_b32 v[12:13], v3 offset0:16 offset1:24
	ds_read2_b32 v[14:15], v3 offset0:82 offset1:90
	ds_read2_b32 v[16:17], v3 offset0:115 offset1:123
	ds_read2_b32 v[18:19], v3 offset0:148 offset1:156
	ds_read2_b32 v[20:21], v3 offset0:181 offset1:189
	ds_read2_b32 v[22:23], v3 offset0:214 offset1:222
	ds_read2_b32 v[28:29], v3 offset0:247 offset1:255
	v_lshl_add_u64 v[8:9], v[24:25], 0, v[8:9]
	global_store_dwordx4 v[8:9], v[4:7], off sc1
	v_add_u32_e32 v8, 16, v26
	v_ashrrev_i32_e32 v9, 31, v8
	v_lshlrev_b64 v[8:9], 11, v[8:9]
	s_waitcnt lgkmcnt(6)
	v_cvt_pk_bf16_f32 v4, v12, v10
	s_waitcnt lgkmcnt(4)
	v_cvt_pk_bf16_f32 v5, v14, v16
	s_waitcnt lgkmcnt(2)
	v_cvt_pk_bf16_f32 v6, v18, v20
	s_waitcnt lgkmcnt(0)
	v_cvt_pk_bf16_f32 v7, v22, v28
	v_lshl_add_u64 v[8:9], v[24:25], 0, v[8:9]
	global_store_dwordx4 v[8:9], v[4:7], off sc1
	v_add_u32_e32 v8, 24, v26
	v_ashrrev_i32_e32 v9, 31, v8
	v_lshlrev_b64 v[8:9], 11, v[8:9]
	v_cvt_pk_bf16_f32 v4, v13, v11
	v_cvt_pk_bf16_f32 v5, v15, v17
	v_cvt_pk_bf16_f32 v6, v19, v21
	v_cvt_pk_bf16_f32 v7, v23, v29
	v_lshl_add_u64 v[8:9], v[24:25], 0, v[8:9]
	global_store_dwordx4 v[8:9], v[4:7], off sc1
	s_waitcnt lgkmcnt(0)
	s_waitcnt vmcnt(0)
	s_barrier
	s_and_saveexec_b64 s[4:5], vcc
	s_cbranch_execz .LBB0_65
	s_mov_b64 s[30:31], exec
	v_mbcnt_lo_u32_b32 v1, s30, 0
	v_mbcnt_hi_u32_b32 v1, s31, v1
	v_cmp_eq_u32_e32 vcc, 0, v1
	s_nop 0
	s_waitcnt vmcnt(0)
	s_and_saveexec_b64 s[12:13], vcc
	s_cbranch_execz .LBB0_63
	s_bcnt1_i32_b64 s26, s[30:31]
	v_mov_b32_e32 v1, 0x28000
	v_mov_b32_e32 v3, s26
	global_atomic_add v1, v3, s[16:17]

.LBB0_70:
	s_or_b64 exec, exec, s[4:5]
	v_mul_f32_e32 v6, v18, v18
	v_fmamk_f32 v15, v6, 0xb94c1982, v1
	v_fmaak_f32 v15, v6, v15, 0xbe2aaa9d
	v_mul_f32_e32 v15, v6, v15
	v_fmac_f32_e32 v18, v18, v15
	v_fmamk_f32 v15, v6, 0x37d75334, v8
	v_fmaak_f32 v15, v6, v15, 0x3d2aabf7
	v_fmaak_f32 v15, v6, v15, 0xbf000004
	v_fma_f32 v6, v6, v15, 1.0
	v_and_b32_e32 v15, 1, v17
	v_cmp_eq_u32_e64 s[4:5], 0, v15
	v_lshlrev_b32_e32 v15, 30, v17
	v_and_b32_e32 v15, 0x80000000, v15
	v_xor_b32_e32 v13, v14, v13
	v_cndmask_b32_e64 v6, v6, v18, s[4:5]
	v_xor_b32_e32 v13, v13, v15
	v_xor_b32_e32 v6, v13, v6
	v_cndmask_b32_e32 v6, v11, v6, vcc
	v_add_co_u32_e32 v14, vcc, 0x1000, v4
	s_nop 1
	v_addc_co_u32_e32 v15, vcc, 0, v5, vcc
	global_store_dword v[14:15], v6, off sc1
	v_add_u32_e32 v6, 0x200, v12
	v_cmp_lt_i32_e32 vcc, s48, v12
	v_lshl_add_u64 v[4:5], v[4:5], 0, s[34:35]
	s_or_b64 s[30:31], vcc, s[30:31]
	v_mov_b32_e32 v12, v6
	s_andn2_b64 exec, exec, s[30:31]
	s_cbranch_execz .LBB0_79

.LBB0_73:
	s_or_saveexec_b64 s[4:5], s[36:37]
	v_mul_f32_e64 v6, |v13|, s44
	v_rndne_f32_e32 v6, v6
	s_xor_b64 exec, exec, s[4:5]
	v_cvt_i32_f32_e32 v17, v6
	v_fma_f32 v18, v6, s45, |v13|
	v_fmac_f32_e32 v18, 0xb3a22168, v6
	v_fmac_f32_e32 v18, 0xa7c234c4, v6
	s_or_b64 exec, exec, s[4:5]
	v_mul_f32_e32 v19, v18, v18
	v_fmamk_f32 v20, v19, 0xb94c1982, v1
	v_fmaak_f32 v20, v19, v20, 0xbe2aaa9d
	v_mul_f32_e32 v20, v19, v20
	v_fmac_f32_e32 v18, v18, v20
	v_fmamk_f32 v20, v19, 0x37d75334, v8
	v_fmaak_f32 v20, v19, v20, 0x3d2aabf7
	v_fmaak_f32 v20, v19, v20, 0xbf000004
	v_fma_f32 v19, v19, v20, 1.0
	v_and_b32_e32 v20, 1, v17
	v_cmp_eq_u32_e32 vcc, 0, v20
	v_lshlrev_b32_e32 v17, 30, v17
	s_nop 0
	v_cndmask_b32_e64 v18, -v18, v19, vcc
	v_bitop3_b32 v17, v17, v18, s46 bitop3:0x6c
	v_cmp_class_f32_e64 vcc, v13, s47
	s_nop 1
	v_cndmask_b32_e32 v17, v11, v17, vcc
	global_store_dword v[4:5], v17, off sc1
	s_and_saveexec_b64 s[4:5], s[10:11]
	s_xor_b64 s[36:37], exec, s[4:5]
	s_cbranch_execz .LBB0_77
	v_cmp_lt_u32_e64 s[4:5], 63, v16
	s_nop 1
	v_cndmask_b32_e64 v6, 0, v9, s[4:5]
	v_add_u32_e32 v6, v6, v16
	v_cmp_lt_u32_e64 s[6:7], 31, v6
	s_nop 1
	v_cndmask_b32_e64 v16, 0, v10, s[6:7]
	v_add_u32_e32 v6, v16, v6
	v_cmp_lt_u32_e64 s[8:9], 31, v6
	s_nop 1
	v_cndmask_b32_e64 v16, 0, v10, s[8:9]
	v_add_u32_e32 v30, v16, v6
	v_mad_u64_u32 v[16:17], s[10:11], v15, s27, 0
	v_mov_b32_e32 v6, v17
	v_mad_u64_u32 v[18:19], s[10:11], v15, s29, v[6:7]
	v_mov_b32_e32 v6, v19
	v_mad_u64_u32 v[20:21], s[10:11], v15, s38, v[6:7]
	v_mov_b32_e32 v6, v21
	v_mad_u64_u32 v[22:23], s[10:11], v15, s39, v[6:7]
	v_mov_b32_e32 v6, v23
	v_mad_u64_u32 v[24:25], s[10:11], v15, s40, v[6:7]
	v_mov_b32_e32 v6, v25
	v_mad_u64_u32 v[26:27], s[10:11], v15, s41, v[6:7]
	v_mov_b32_e32 v6, v27
	v_mad_u64_u32 v[28:29], s[10:11], v15, s42, v[6:7]
	v_cndmask_b32_e64 v17, v26, v22, s[4:5]
	v_cndmask_b32_e64 v6, v28, v24, s[4:5]
	v_cndmask_b32_e64 v19, v29, v26, s[4:5]
	v_cndmask_b32_e64 v15, v6, v17, s[6:7]
	v_cndmask_b32_e64 v6, v19, v6, s[6:7]
	v_cndmask_b32_e64 v19, v24, v20, s[4:5]
	v_cndmask_b32_e64 v17, v17, v19, s[6:7]
	v_cndmask_b32_e64 v18, v22, v18, s[4:5]
	v_cndmask_b32_e64 v6, v6, v15, s[8:9]
	v_cndmask_b32_e64 v15, v15, v17, s[8:9]
	v_sub_u32_e32 v21, 32, v30
	v_cndmask_b32_e64 v19, v19, v18, s[6:7]
	v_alignbit_b32 v23, v6, v15, v21
	v_cmp_eq_u32_e64 s[10:11], 0, v30
	v_cndmask_b32_e64 v17, v17, v19, s[8:9]
	v_alignbit_b32 v22, v15, v17, v21
	v_cndmask_b32_e64 v6, v23, v6, s[10:11]
	v_cndmask_b32_e64 v16, v20, v16, s[4:5]
	v_cndmask_b32_e64 v15, v22, v15, s[10:11]
	v_bfe_u32 v24, v6, 29, 1
	v_cndmask_b32_e64 v16, v18, v16, s[6:7]
	v_alignbit_b32 v22, v6, v15, 30
	v_sub_u32_e32 v25, 0, v24
	v_cndmask_b32_e64 v16, v19, v16, s[8:9]
	v_xor_b32_e32 v22, v22, v25
	v_alignbit_b32 v18, v17, v16, v21
	v_cndmask_b32_e64 v17, v18, v17, s[10:11]
	v_ffbh_u32_e32 v18, v22
	v_alignbit_b32 v15, v15, v17, 30
	v_min_u32_e32 v18, 32, v18
	v_alignbit_b32 v16, v17, v16, 30
	v_xor_b32_e32 v15, v15, v25
	v_sub_u32_e32 v19, 31, v18
	v_xor_b32_e32 v16, v16, v25
	v_alignbit_b32 v20, v22, v15, v19
	v_alignbit_b32 v15, v15, v16, v19
	v_alignbit_b32 v16, v20, v15, 9
	v_ffbh_u32_e32 v17, v16
	v_min_u32_e32 v17, 32, v17
	v_lshrrev_b32_e32 v23, 29, v6
	v_not_b32_e32 v19, v17
	v_alignbit_b32 v15, v16, v15, v19
	v_lshlrev_b32_e32 v16, 31, v23
	v_or_b32_e32 v19, 0x33000000, v16
	v_add_lshl_u32 v17, v17, v18, 23
	v_lshrrev_b32_e32 v15, 9, v15
	v_sub_u32_e32 v17, v19, v17
	v_or_b32_e32 v16, 0.5, v16
	v_lshlrev_b32_e32 v18, 23, v18
	v_or_b32_e32 v15, v17, v15
	v_lshrrev_b32_e32 v17, 9, v20
	v_sub_u32_e32 v16, v16, v18
	v_or_b32_e32 v16, v17, v16
	v_mul_f32_e32 v17, 0x3fc90fda, v16
	v_fma_f32 v18, v16, s43, -v17
	v_fmac_f32_e32 v18, 0x33a22168, v16
	v_fmac_f32_e32 v18, 0x3fc90fda, v15
	v_lshrrev_b32_e32 v6, 30, v6
	v_add_f32_e32 v18, v17, v18
	v_add_u32_e32 v17, v24, v6

.LBB0_83:
	v_ashrrev_i32_e32 v5, 31, v4
	v_lshl_add_u64 v[14:15], v[4:5], 2, s[18:19]
	global_load_dwordx4 v[6:9], v[14:15], off nt
	global_load_dwordx4 v[10:13], v[14:15], off offset:16 nt
	s_addk_i32 s6, 0x1f0
	v_lshl_add_u64 v[14:15], v[4:5], 1, s[4:5]
	s_cmpk_lt_i32 s6, 0xfe90
	v_add_u32_e32 v4, 0x3e000, v4
	s_waitcnt vmcnt(1)
	v_cvt_pk_bf16_f32 v6, v6, v7
	v_cvt_pk_bf16_f32 v7, v8, v9
	s_waitcnt vmcnt(0)
	v_cvt_pk_bf16_f32 v8, v10, v11
	v_cvt_pk_bf16_f32 v9, v12, v13
	global_store_dwordx4 v[14:15], v[6:9], off sc1
	s_cbranch_scc1 .LBB0_83

.LBB0_86:
	s_lshl_b32 s6, s13, 6
	v_add_u32_e32 v34, s6, v1
	v_lshl_add_u64 v[16:17], s[4:5], 2, v[4:5]
	v_mad_i64_i32 v[18:19], s[14:15], v34, s11, v[16:17]
	v_add_u32_e32 v20, 2, v34
	v_add_u32_e32 v22, 4, v34
	v_add_u32_e32 v24, 6, v34
	v_add_u32_e32 v26, 8, v34
	v_add_u32_e32 v28, 10, v34
	v_add_u32_e32 v30, 12, v34
	v_add_u32_e32 v32, 14, v34
	v_mad_i64_i32 v[20:21], s[14:15], v20, s11, v[16:17]
	v_mad_i64_i32 v[22:23], s[14:15], v22, s11, v[16:17]
	v_mad_i64_i32 v[24:25], s[14:15], v24, s11, v[16:17]
	v_mad_i64_i32 v[26:27], s[14:15], v26, s11, v[16:17]
	v_mad_i64_i32 v[28:29], s[14:15], v28, s11, v[16:17]
	v_mad_i64_i32 v[30:31], s[14:15], v30, s11, v[16:17]
	v_mad_i64_i32 v[32:33], s[14:15], v32, s11, v[16:17]
	global_load_dword v35, v[18:19], off nt
	global_load_dword v36, v[20:21], off nt
	global_load_dword v37, v[22:23], off nt
	global_load_dword v38, v[24:25], off nt
	global_load_dword v39, v[26:27], off nt
	global_load_dword v40, v[28:29], off nt
	global_load_dword v41, v[30:31], off nt
	global_load_dword v42, v[32:33], off nt
	v_add_u32_e32 v18, 16, v34
	v_mad_i64_i32 v[18:19], s[14:15], v18, s11, v[16:17]
	v_add_u32_e32 v20, 18, v34
	v_add_u32_e32 v22, 20, v34
	v_add_u32_e32 v24, 22, v34
	v_add_u32_e32 v26, 24, v34
	v_add_u32_e32 v28, 26, v34
	v_add_u32_e32 v30, 28, v34
	v_add_u32_e32 v32, 30, v34
	v_mad_i64_i32 v[20:21], s[14:15], v20, s11, v[16:17]
	v_mad_i64_i32 v[22:23], s[14:15], v22, s11, v[16:17]
	v_mad_i64_i32 v[24:25], s[14:15], v24, s11, v[16:17]
	v_mad_i64_i32 v[26:27], s[14:15], v26, s11, v[16:17]
	v_mad_i64_i32 v[28:29], s[14:15], v28, s11, v[16:17]
	v_mad_i64_i32 v[30:31], s[14:15], v30, s11, v[16:17]
	v_mad_i64_i32 v[32:33], s[14:15], v32, s11, v[16:17]
	global_load_dword v43, v[18:19], off nt
	global_load_dword v44, v[20:21], off nt
	global_load_dword v45, v[22:23], off nt
	global_load_dword v46, v[24:25], off nt
	global_load_dword v47, v[26:27], off nt
	global_load_dword v48, v[28:29], off nt
	global_load_dword v49, v[30:31], off nt
	global_load_dword v50, v[32:33], off nt
	v_add_u32_e32 v18, 32, v34
	v_mad_i64_i32 v[18:19], s[14:15], v18, s11, v[16:17]
	v_add_u32_e32 v20, 34, v34
	v_add_u32_e32 v22, 36, v34
	v_add_u32_e32 v24, 38, v34
	v_add_u32_e32 v26, 40, v34
	v_add_u32_e32 v28, 42, v34
	v_add_u32_e32 v30, 44, v34
	v_add_u32_e32 v32, 46, v34
	v_mad_i64_i32 v[20:21], s[14:15], v20, s11, v[16:17]
	v_mad_i64_i32 v[22:23], s[14:15], v22, s11, v[16:17]
	v_mad_i64_i32 v[24:25], s[14:15], v24, s11, v[16:17]
	v_mad_i64_i32 v[26:27], s[14:15], v26, s11, v[16:17]
	v_mad_i64_i32 v[28:29], s[14:15], v28, s11, v[16:17]
	v_mad_i64_i32 v[30:31], s[14:15], v30, s11, v[16:17]
	v_mad_i64_i32 v[32:33], s[14:15], v32, s11, v[16:17]
	global_load_dword v51, v[18:19], off nt
	global_load_dword v52, v[20:21], off nt
	global_load_dword v53, v[22:23], off nt
	global_load_dword v54, v[24:25], off nt
	global_load_dword v55, v[26:27], off nt
	global_load_dword v56, v[28:29], off nt
	global_load_dword v57, v[30:31], off nt
	global_load_dword v58, v[32:33], off nt
	v_add_u32_e32 v18, 48, v34
	v_mad_i64_i32 v[18:19], s[14:15], v18, s11, v[16:17]
	v_add_u32_e32 v20, 50, v34
	v_add_u32_e32 v22, 52, v34
	v_add_u32_e32 v24, 54, v34
	v_add_u32_e32 v26, 56, v34
	v_add_u32_e32 v28, 58, v34
	v_add_u32_e32 v30, 60, v34
	v_add_u32_e32 v32, 62, v34
	v_mad_i64_i32 v[20:21], s[14:15], v20, s11, v[16:17]
	v_mad_i64_i32 v[22:23], s[14:15], v22, s11, v[16:17]
	v_mad_i64_i32 v[24:25], s[14:15], v24, s11, v[16:17]
	v_mad_i64_i32 v[26:27], s[14:15], v26, s11, v[16:17]
	v_mad_i64_i32 v[28:29], s[14:15], v28, s11, v[16:17]
	v_mad_i64_i32 v[30:31], s[14:15], v30, s11, v[16:17]
	v_mad_i64_i32 v[16:17], s[14:15], v32, s11, v[16:17]
	global_load_dword v32, v[18:19], off nt
	global_load_dword v33, v[20:21], off nt
	global_load_dword v34, v[22:23], off nt
	global_load_dword v59, v[24:25], off nt
	global_load_dword v60, v[26:27], off nt
	global_load_dword v61, v[28:29], off nt
	global_load_dword v62, v[30:31], off nt
	global_load_dword v63, v[16:17], off nt
	s_waitcnt vmcnt(30)
	ds_write2_b32 v8, v35, v36 offset1:66
	s_waitcnt vmcnt(28)
	ds_write2_b32 v8, v37, v38 offset0:132 offset1:198
	s_waitcnt vmcnt(26)
	ds_write2_b32 v9, v39, v40 offset0:8 offset1:74
	s_waitcnt vmcnt(24)
	ds_write2_b32 v9, v41, v42 offset0:140 offset1:206
	s_waitcnt vmcnt(22)
	ds_write2_b32 v10, v43, v44 offset0:16 offset1:82
	s_waitcnt vmcnt(20)
	ds_write2_b32 v10, v45, v46 offset0:148 offset1:214
	s_waitcnt vmcnt(18)
	ds_write2_b32 v11, v47, v48 offset0:24 offset1:90
	s_waitcnt vmcnt(16)
	ds_write2_b32 v11, v49, v50 offset0:156 offset1:222
	s_waitcnt vmcnt(14)
	ds_write2_b32 v12, v51, v52 offset0:32 offset1:98
	s_waitcnt vmcnt(12)
	ds_write2_b32 v12, v53, v54 offset0:164 offset1:230
	s_waitcnt vmcnt(10)
	ds_write2_b32 v13, v55, v56 offset0:40 offset1:106
	s_waitcnt vmcnt(8)
	ds_write2_b32 v13, v57, v58 offset0:172 offset1:238
	s_waitcnt vmcnt(6)
	ds_write2_b32 v14, v32, v33 offset0:48 offset1:114
	s_waitcnt vmcnt(4)
	ds_write2_b32 v14, v34, v59 offset0:180 offset1:246
	s_waitcnt vmcnt(2)
	ds_write2_b32 v15, v60, v61 offset0:56 offset1:122
	s_waitcnt vmcnt(0)
	ds_write2_b32 v15, v62, v63 offset0:188 offset1:254
	s_waitcnt lgkmcnt(0)
	ds_read2_b32 v[20:21], v7 offset0:33 offset1:41
	ds_read2_b32 v[22:23], v7 offset1:8
	ds_read2_b32 v[24:25], v7 offset0:66 offset1:74
	ds_read2_b32 v[26:27], v7 offset0:99 offset1:107
	ds_read2_b32 v[28:29], v7 offset0:132 offset1:140
	ds_read2_b32 v[30:31], v7 offset0:165 offset1:173
	ds_read2_b32 v[32:33], v7 offset0:198 offset1:206
	ds_read2_b32 v[34:35], v7 offset0:231 offset1:239
	s_add_i32 s4, s9, s12
	v_add_u32_e32 v40, s4, v6
	v_add_u32_e32 v38, 0x600, v40
	s_ashr_i32 s7, s6, 31
	v_ashrrev_i32_e32 v39, 31, v38
	v_lshl_add_u64 v[36:37], s[6:7], 1, v[2:3]
	v_lshlrev_b64 v[38:39], 11, v[38:39]
	s_waitcnt lgkmcnt(6)
	v_cvt_pk_bf16_f32 v16, v22, v20
	s_waitcnt lgkmcnt(4)
	v_cvt_pk_bf16_f32 v17, v24, v26
	s_waitcnt lgkmcnt(2)
	v_cvt_pk_bf16_f32 v18, v28, v30
	s_waitcnt lgkmcnt(0)
	v_cvt_pk_bf16_f32 v19, v32, v34
	v_lshl_add_u64 v[38:39], v[36:37], 0, v[38:39]
	v_add_u32_e32 v20, 0x608, v40
	global_store_dwordx4 v[38:39], v[16:19], off sc1
	s_add_i32 s4, s8, 0x1f0
	s_addk_i32 s9, 0x3e00
	v_cvt_pk_bf16_f32 v16, v23, v21
	v_ashrrev_i32_e32 v21, 31, v20
	v_cvt_pk_bf16_f32 v17, v25, v27
	v_cvt_pk_bf16_f32 v18, v29, v31
	v_cvt_pk_bf16_f32 v19, v33, v35
	v_lshlrev_b64 v[20:21], 11, v[20:21]
	ds_read2_b32 v[22:23], v7 offset0:49 offset1:57
	ds_read2_b32 v[24:25], v7 offset0:16 offset1:24
	ds_read2_b32 v[26:27], v7 offset0:82 offset1:90
	ds_read2_b32 v[28:29], v7 offset0:115 offset1:123
	ds_read2_b32 v[30:31], v7 offset0:148 offset1:156
	ds_read2_b32 v[32:33], v7 offset0:181 offset1:189
	ds_read2_b32 v[34:35], v7 offset0:214 offset1:222
	ds_read2_b32 v[38:39], v7 offset0:247 offset1:255
	v_lshl_add_u64 v[20:21], v[36:37], 0, v[20:21]
	global_store_dwordx4 v[20:21], v[16:19], off sc1
	v_add_u32_e32 v20, 0x610, v40
	v_ashrrev_i32_e32 v21, 31, v20
	v_lshlrev_b64 v[20:21], 11, v[20:21]
	s_waitcnt lgkmcnt(6)
	v_cvt_pk_bf16_f32 v16, v24, v22
	s_waitcnt lgkmcnt(4)
	v_cvt_pk_bf16_f32 v17, v26, v28
	s_waitcnt lgkmcnt(2)
	v_cvt_pk_bf16_f32 v18, v30, v32
	s_waitcnt lgkmcnt(0)
	v_cvt_pk_bf16_f32 v19, v34, v38
	v_lshl_add_u64 v[20:21], v[36:37], 0, v[20:21]
	global_store_dwordx4 v[20:21], v[16:19], off sc1
	v_add_u32_e32 v20, 0x618, v40
	v_ashrrev_i32_e32 v21, 31, v20
	v_lshlrev_b64 v[20:21], 11, v[20:21]
	v_cvt_pk_bf16_f32 v16, v25, v23
	v_cvt_pk_bf16_f32 v17, v27, v29
	v_cvt_pk_bf16_f32 v18, v31, v33
	v_cvt_pk_bf16_f32 v19, v35, v39
	v_lshl_add_u64 v[20:21], v[36:37], 0, v[20:21]
	global_store_dwordx4 v[20:21], v[16:19], off sc1
	s_waitcnt lgkmcnt(0)
	s_addk_i32 s10, 0x7c00
	s_cmpk_lt_i32 s8, 0x310
	s_mov_b32 s8, s4
	s_cbranch_scc0 .LBB0_113

.LBB0_113:
	s_cmpk_lt_i32 s3, 0xc0
	s_cbranch_scc1 .LBB0_118
	s_waitcnt vmcnt(0)
	v_cmp_eq_u32_e32 vcc, 0, v0
	s_waitcnt lgkmcnt(0)
	s_barrier
	s_and_saveexec_b64 s[4:5], vcc
	s_cbranch_execz .LBB0_117
	s_mov_b64 s[6:7], exec
	v_mbcnt_lo_u32_b32 v0, s6, 0
	v_mbcnt_hi_u32_b32 v0, s7, v0
	v_cmp_eq_u32_e32 vcc, 0, v0
	s_and_b64 s[8:9], exec, vcc
	s_nop 0
	s_waitcnt vmcnt(0)
	s_mov_b64 exec, s[8:9]
	s_cbranch_execz .LBB0_117
	s_bcnt1_i32_b64 s3, s[6:7]
	v_mov_b32_e32 v0, 0x28000
	v_mov_b32_e32 v1, s3
	global_atomic_add v0, v1, s[16:17] offset:256
